# grid barrier: the acquire-side L1 invalidate is issued together with the arrival atomic (all waves already drained and parked) instead of after the release is seen, so its latency overlaps the arrival
# speedup vs baseline: 1.0053x; 1.0037x over previous
; __device__ __forceinline__ unsigned xb_add(unsigned* p, unsigned v) { return __hip_atomic_fetch_add(p, v, __ATOMIC_RELAXED, __HIP_MEMORY_SCOPE_AGENT); }
; __device__ __forceinline__ void xcd_barrier(const XcdBarrier& b, const int tid) {
;     ...
;         const unsigned old = xb_add(&bar[XB_XSUB(b.x)], 1u);
;         const unsigned gen = old / nloc;
.LBB0_586:
	s_mov_b64 s[4:5], exec
	v_mbcnt_lo_u32_b32 v0, s4, 0
	v_mbcnt_hi_u32_b32 v0, s5, v0
	v_cmp_eq_u32_e32 vcc, 0, v0
	s_and_saveexec_b64 s[2:3], vcc
	s_cbranch_execz .LBB0_588
	s_bcnt1_i32_b64 s4, s[4:5]
	v_mov_b32_e32 v4, s4
	v_readlane_b32 s4, v250, 9
	v_readlane_b32 s5, v250, 10
	s_nop 4
	global_atomic_add v4, v1, v4, s[4:5] sc0
	buffer_inv sc1

; __device__ __forceinline__ unsigned xb_ld(unsigned* p)              { return __hip_atomic_load(p, __ATOMIC_RELAXED, __HIP_MEMORY_SCOPE_AGENT); }
; #define XB_SPIN(cond, bar) do { unsigned _sp = 0; while (cond) { __builtin_amdgcn_s_sleep(1); \
;     if ((++_sp & 255u) == 0u) { if (xb_ld(&(bar)[XB_TMO])) break; if (_sp > XB_SPIN_CAP) { atomicAdd(&(bar)[XB_TMO], 1u); break; } } } } while (0)
; __device__ __forceinline__ void xcd_barrier(const XcdBarrier& b, const int tid) {
;     ...
;         } else {
;             XB_SPIN(xb_ld(&bar[XB_XGEN(b.x)]) == gen, bar);
;             __builtin_amdgcn_fence(__ATOMIC_ACQUIRE, "agent");
;             asm volatile("s_waitcnt vmcnt(0)" ::: "memory");
;         }
.LBB0_601:
	s_or_b64 exec, exec, s[4:5]
	s_waitcnt vmcnt(0)
	s_waitcnt vmcnt(0)

; __device__ __forceinline__ unsigned xb_ld(unsigned* p)              { return __hip_atomic_load(p, __ATOMIC_RELAXED, __HIP_MEMORY_SCOPE_AGENT); }
; __device__ __forceinline__ unsigned xb_add(unsigned* p, unsigned v) { return __hip_atomic_fetch_add(p, v, __ATOMIC_RELAXED, __HIP_MEMORY_SCOPE_AGENT); }
; #define XB_SPIN(cond, bar) do { unsigned _sp = 0; while (cond) { __builtin_amdgcn_s_sleep(1); \
;     if ((++_sp & 255u) == 0u) { if (xb_ld(&(bar)[XB_TMO])) break; if (_sp > XB_SPIN_CAP) { atomicAdd(&(bar)[XB_TMO], 1u); break; } } } } while (0)
; __device__ __forceinline__ void xcd_barrier(const XcdBarrier& b, const int tid) {
;     ...
;             __builtin_amdgcn_fence(__ATOMIC_RELEASE, "agent");
;             asm volatile("s_waitcnt vmcnt(0)" ::: "memory");
;             const unsigned og = xb_add(&bar[XB_TOP], 1u);
;             const unsigned tg = og / nx;
;             if (og + 1u == (tg + 1u) * nx) xb_add(&bar[XB_TOPGEN], 1u);
;             else XB_SPIN(xb_ld(&bar[XB_TOPGEN]) == tg, bar);
;             __builtin_amdgcn_fence(__ATOMIC_ACQUIRE, "agent");
;             xb_add(&bar[XB_XGEN(b.x)], 1u);
;             asm volatile("s_waitcnt vmcnt(0)" ::: "memory");
.LBB0_619:
	s_or_b64 exec, exec, s[2:3]
	s_mov_b64 s[2:3], exec
	v_mbcnt_lo_u32_b32 v0, s2, 0
	v_mbcnt_hi_u32_b32 v0, s3, v0
	v_cmp_eq_u32_e32 vcc, 0, v0
	s_waitcnt vmcnt(0)
	s_and_saveexec_b64 s[4:5], vcc
	s_cbranch_execz .LBB0_621
	s_bcnt1_i32_b64 s2, s[2:3]
	v_mov_b32_e32 v0, s2
	v_readlane_b32 s2, v250, 11
	v_readlane_b32 s3, v250, 12
	s_nop 4
	s_nop 0
